# FoX epilogue: stale just-in-time gate waits removed (they waited on stores), next-unit loads issued after the gate rows and left in flight (counted waits)
# speedup vs baseline: 1.0252x; 1.0252x over previous
.Lmy_pf_k:
	s_waitcnt vmcnt(4)
	v_mov_b32_e32 v16, v150
	s_cmp_gt_u32 s34, 63
	s_cbranch_scc1 .Lmy_pf_k2
	v_mov_b32_e32 v14, v151
	v_mov_b32_e32 v12, v152
	v_mov_b32_e32 v13, v153
	v_mov_b32_e32 v0, v154
	v_mov_b32_e32 v1, v155
	v_mov_b32_e32 v2, v156
	v_mov_b32_e32 v3, v157

.LBB0_307:
	s_cmp_lg_u32 0, -1
	s_cselect_b32 s1, 0, 0
	s_addk_i32 s1, 0x6000
	v_add3_u32 v64, v185, s1, v183
	v_cvt_pk_bf16_f32 v68, v48, v49
	v_cvt_pk_bf16_f32 v69, v50, v51
	v_cvt_pk_bf16_f32 v70, v52, v53
	v_cvt_pk_bf16_f32 v71, v54, v55
	v_cvt_pk_bf16_f32 v72, v56, v57
	v_cvt_pk_bf16_f32 v73, v58, v59
	v_cvt_pk_bf16_f32 v74, v60, v61
	v_cvt_pk_bf16_f32 v75, v62, v63
	v_cvt_pk_bf16_f32 v76, v32, v33
	v_cvt_pk_bf16_f32 v77, v34, v35
	v_cvt_pk_bf16_f32 v78, v36, v37
	v_cvt_pk_bf16_f32 v79, v38, v39
	v_cvt_pk_bf16_f32 v80, v40, v41
	v_cvt_pk_bf16_f32 v81, v42, v43
	v_cvt_pk_bf16_f32 v82, v44, v45
	v_cvt_pk_bf16_f32 v83, v46, v47
	v_add3_u32 v64, v64, v186, s34
	ds_read_b64_tr_b16 v[84:85],v64 offset:0
	ds_read_b64_tr_b16 v[86:87],v64 offset:512
	ds_read_b64_tr_b16 v[88:89],v64 offset:1024
	ds_read_b64_tr_b16 v[90:91],v64 offset:1536
	ds_read_b64_tr_b16 v[92:93],v64 offset:2048
	ds_read_b64_tr_b16 v[94:95],v64 offset:2560
	ds_read_b64_tr_b16 v[96:97],v64 offset:3072
	ds_read_b64_tr_b16 v[98:99],v64 offset:3584
	s_waitcnt lgkmcnt(0)
	s_nop 0
	v_mfma_f32_32x32x16_bf16 v[0:15], v[68:71], v[84:87], v[0:15]
	ds_read_b64_tr_b16 v[84:85],v64 offset:4096
	ds_read_b64_tr_b16 v[86:87],v64 offset:4608
	v_mfma_f32_32x32x16_bf16 v[0:15], v[72:75], v[88:91], v[0:15]
	ds_read_b64_tr_b16 v[88:89],v64 offset:5120
	ds_read_b64_tr_b16 v[90:91],v64 offset:5632
	v_mfma_f32_32x32x16_bf16 v[0:15], v[76:79], v[92:95], v[0:15]
	ds_read_b64_tr_b16 v[92:93],v64 offset:6144
	ds_read_b64_tr_b16 v[94:95],v64 offset:6656
	v_mfma_f32_32x32x16_bf16 v[0:15], v[80:83], v[96:99], v[0:15]
	ds_read_b64_tr_b16 v[96:97],v64 offset:7168
	ds_read_b64_tr_b16 v[98:99],v64 offset:7680
	s_waitcnt lgkmcnt(0)
	v_mfma_f32_32x32x16_bf16 v[16:31], v[68:71], v[84:87], v[16:31]
	v_cmp_eq_u32_e32 vcc, 0, v181
	v_mov_b32_e32 v64, 0
	v_mfma_f32_32x32x16_bf16 v[16:31], v[72:75], v[88:91], v[16:31]
	v_mfma_f32_32x32x16_bf16 v[16:31], v[76:79], v[92:95], v[16:31]
	v_mfma_f32_32x32x16_bf16 v[16:31], v[80:83], v[96:99], v[16:31]
	v_mov_b32_e32 v64, v201
	s_add_u32 s100, s12, s92
	s_addc_u32 s101, s13, s93
	v_ashrrev_i32_e32 v244, 3, v178
	v_mov_b32_e32 v245, 0
	v_lshl_add_u64 v[244:245], s[42:43], 0, v[244:245]
	v_lshlrev_b64 v[244:245], 11, v[244:245]
	v_lshlrev_b32_e32 v246, 4, v178
	v_and_b32_e32 v246, 0x70, v246
	v_mov_b32_e32 v247, 0
	v_lshl_add_u64 v[246:247], s[100:101], 0, v[246:247]
	v_lshl_add_u64 v[244:245], v[246:247], 0, v[244:245]
	s_mov_b32 s100, 0x4000
	s_mov_b32 s101, 0
	global_load_dwordx4 v[208:211], v[244:245], off
	v_lshl_add_u64 v[244:245], v[244:245], 0, s[100:101]
	global_load_dwordx4 v[226:229], v[244:245], off
	v_lshl_add_u64 v[244:245], v[244:245], 0, s[100:101]
	global_load_dwordx4 v[230:233], v[244:245], off
	v_lshl_add_u64 v[244:245], v[244:245], 0, s[100:101]
	global_load_dwordx4 v[234:237], v[244:245], off
	v_mov_b32_e32 v246, 0x1c9f0
	ds_read_b32 v246, v246
	v_writelane_b32 v241, s16, 30
	v_writelane_b32 v241, s17, 31
	v_writelane_b32 v241, s18, 32
	v_writelane_b32 v241, s19, 33
	v_writelane_b32 v241, s20, 34
	v_writelane_b32 v241, s21, 35
	s_waitcnt lgkmcnt(0)
	v_readfirstlane_b32 s100, v246
	s_mov_b32 s101, -1
	s_cmpk_lt_u32 s100, 0x200
	s_cbranch_scc0 .Lmy_fox_nopf
	s_add_i32 s100, s100, s98
	s_lshr_b32 s16, s100, 5
	s_and_b32 s16, s16, 0x7fffff0
	s_bfe_u32 s17, s100, 0x40003
	s_or_b32 s16, s16, s17
	s_lshr_b32 s17, s100, 4
	s_and_b32 s17, s17, 24
	s_xor_b32 s17, s17, 31
	s_and_b32 s18, s100, 7
	s_sub_i32 s17, s17, s18
	s_mov_b32 s101, s100
	v_readfirstlane_b32 s100, v181
	s_lshr_b32 s18, s16, 4
	s_lshl_b32 s18, s18, 13
	s_lshl_b32 s19, s17, 8
	s_add_i32 s18, s18, s19
	s_lshr_b32 s19, s100, 1
	s_add_i32 s18, s18, s19
	s_lshl_b32 s18, s18, 11
	s_and_b32 s19, s16, 15
	s_lshl_b32 s19, s19, 7
	s_add_i32 s18, s18, s19
	s_add_u32 s20, s65, s18
	s_addc_u32 s21, s70, 0
	v_lshlrev_b32_e32 v246, 11, v179
	v_lshl_or_b32 v246, v180, 4, v246
	global_load_dwordx4 v[114:117], v246, s[20:21]
	global_load_dwordx4 v[110:113], v246, s[20:21] offset:32
	global_load_dwordx4 v[106:109], v246, s[20:21] offset:64
	global_load_dwordx4 v[102:105], v246, s[20:21] offset:96
	s_add_u32 s20, s14, s18
	s_addc_u32 s21, s15, 0
	global_load_dwordx4 v[134:137], v246, s[20:21] offset:96
	global_load_dwordx4 v[138:141], v246, s[20:21] offset:64
	global_load_dwordx4 v[142:145], v246, s[20:21] offset:32
	global_load_dwordx4 v[146:149], v246, s[20:21]
	s_lshl_b32 s18, s16, 15
	s_lshl_b32 s19, s17, 10
	s_add_i32 s18, s18, s19
	s_lshl_b32 s19, s100, 1
	s_add_i32 s18, s18, s19
	s_add_u32 s20, s4, s18
	s_addc_u32 s21, s5, 0
	v_lshlrev_b32_e32 v247, 2, v179
	global_load_dword v150, v247, s[20:21]
	s_cmp_lg_u32 s100, 0
	s_cbranch_scc1 .Lmy_fox_pf9
	v_lshl_or_b32 v247, s16, 6, v178
	v_lshlrev_b32_e32 v247, 2, v247
	global_load_dword v151, v247, s[26:27]
	s_add_i32 s18, s16, 0x80
	s_lshl_b32 s18, s18, 9
	s_add_u32 s20, s35, s18
	s_addc_u32 s21, s80, 0
	v_lshlrev_b32_e32 v247, 3, v178
	global_load_dwordx2 v[152:153], v247, s[20:21]
	s_lshl_b32 s18, s16, 9
	s_lshl_b32 s19, s17, 4
	s_add_i32 s18, s18, s19
	s_add_u32 s20, s35, s18
	s_addc_u32 s21, s80, 0
	global_load_dwordx4 v[154:157], v101, s[20:21]
	s_mov_b32 s100, 12
	s_branch .Lmy_fox_pfe
.Lmy_fox_pf9:
	s_mov_b32 s100, 9
	s_branch .Lmy_fox_pfe
.Lmy_fox_nopf:
	s_mov_b32 s100, 0
.Lmy_fox_pfe:
	v_writelane_b32 v241, s101, 36
	v_readlane_b32 s16, v241, 30
	v_readlane_b32 s17, v241, 31
	v_readlane_b32 s18, v241, 32
	v_readlane_b32 s19, v241, 33
	v_readlane_b32 s20, v241, 34
	v_readlane_b32 s21, v241, 35
	v_add_f32_e32 v48, v48, v49
	v_add_f32_e32 v48, v50, v48
	v_add_f32_e32 v48, v51, v48
	v_add_f32_e32 v48, v52, v48
	v_add_f32_e32 v48, v53, v48
	v_add_f32_e32 v48, v54, v48
	v_add_f32_e32 v48, v55, v48
	v_add_f32_e32 v48, v56, v48
	v_add_f32_e32 v48, v57, v48
	v_add_f32_e32 v48, v58, v48
	v_add_f32_e32 v48, v59, v48
	v_add_f32_e32 v48, v60, v48
	v_add_f32_e32 v48, v61, v48
	v_add_f32_e32 v48, v62, v48
	v_add_f32_e32 v48, v63, v48
	v_add_f32_e32 v32, v32, v48
	v_add_f32_e32 v32, v33, v32
	v_add_f32_e32 v32, v34, v32
	v_add_f32_e32 v32, v35, v32
	v_add_f32_e32 v32, v36, v32
	v_add_f32_e32 v32, v37, v32
	v_add_f32_e32 v32, v38, v32
	v_add_f32_e32 v32, v39, v32
	v_add_f32_e32 v32, v40, v32
	v_add_f32_e32 v32, v41, v32
	v_add_f32_e32 v32, v42, v32
	v_add_f32_e32 v32, v43, v32
	v_add_f32_e32 v32, v44, v32
	v_add_f32_e32 v32, v45, v32
	v_add_f32_e32 v32, v46, v32
	v_add_f32_e32 v32, v47, v32
	v_add_f32_e32 v32, v65, v32
	v_mov_b32_e32 v33, v32
	s_nop 1
	v_permlane32_swap_b32_e32 v32, v33
	s_and_saveexec_b64 s[8:9], s[6:7]
	v_lshl_add_u32 v34, v179, 2, s41
	v_add_f32_e32 v32, v32, v33
	ds_write_b32 v34, v32 offset:49280
	s_or_b64 exec, exec, s[8:9]
	s_waitcnt lgkmcnt(0)
	ds_read_b128 v[32:35], v66 offset:49280
	ds_read_b128 v[36:39], v66 offset:49312
	s_lshl_b64 s[6:7], s[10:11], 1
	s_add_u32 s1, s73, s6
	s_addc_u32 s7, s64, s7
	s_waitcnt lgkmcnt(1)
	v_rcp_f32_e32 v40, v32
	s_lshl_b32 s6, s69, 12
	v_rcp_f32_e32 v41, v33
	s_add_i32 s8, s6, 0
	v_lshlrev_b32_e32 v48, 1, v179
	v_lshlrev_b32_e32 v49, 9, v180
	v_mul_f32_e32 v0, v0, v40
	v_add3_u32 v48, s8, v48, v49
	v_cvt_pk_bf16_f32 v0, v0, s0
	v_rcp_f32_e32 v42, v34
	v_rcp_f32_e32 v43, v35
	s_waitcnt lgkmcnt(0)
	v_rcp_f32_e32 v44, v36
	ds_read_b128 v[32:35], v66 offset:49344
	v_rcp_f32_e32 v45, v37
	v_rcp_f32_e32 v46, v38
	v_rcp_f32_e32 v47, v39
	ds_read_b128 v[36:39], v66 offset:49376
	ds_write_b16 v48, v0 offset:51200
	v_mul_f32_e32 v0, v16, v40
	v_cvt_pk_bf16_f32 v0, v0, s0
	ds_write_b16 v48, v0 offset:51264
	v_mul_f32_e32 v0, v1, v41
	v_cvt_pk_bf16_f32 v0, v0, s0
	ds_write_b16 v48, v0 offset:51328
	v_mul_f32_e32 v0, v17, v41
	v_cvt_pk_bf16_f32 v0, v0, s0
	ds_write_b16 v48, v0 offset:51392
	v_mul_f32_e32 v0, v2, v42
	v_cvt_pk_bf16_f32 v0, v0, s0
	ds_write_b16 v48, v0 offset:51456
	v_mul_f32_e32 v0, v18, v42
	v_cvt_pk_bf16_f32 v0, v0, s0
	ds_write_b16 v48, v0 offset:51520
	v_mul_f32_e32 v0, v3, v43
	v_cvt_pk_bf16_f32 v0, v0, s0
	ds_write_b16 v48, v0 offset:51584
	v_mul_f32_e32 v0, v19, v43
	v_cvt_pk_bf16_f32 v0, v0, s0
	ds_write_b16 v48, v0 offset:51648
	v_mul_f32_e32 v0, v4, v44
	v_cvt_pk_bf16_f32 v0, v0, s0
	ds_write_b16 v48, v0 offset:52224
	v_mul_f32_e32 v0, v20, v44
	v_cvt_pk_bf16_f32 v0, v0, s0
	ds_write_b16 v48, v0 offset:52288
	v_mul_f32_e32 v0, v5, v45
	v_cvt_pk_bf16_f32 v0, v0, s0
	ds_write_b16 v48, v0 offset:52352
	v_mul_f32_e32 v0, v21, v45
	v_cvt_pk_bf16_f32 v0, v0, s0
	ds_write_b16 v48, v0 offset:52416
	v_mul_f32_e32 v0, v6, v46
	v_cvt_pk_bf16_f32 v0, v0, s0
	ds_write_b16 v48, v0 offset:52480
	v_mul_f32_e32 v0, v22, v46
	v_cvt_pk_bf16_f32 v0, v0, s0
	s_waitcnt lgkmcnt(14)
	v_rcp_f32_e32 v32, v32
	ds_write_b16 v48, v0 offset:52544
	v_mul_f32_e32 v0, v7, v47
	v_cvt_pk_bf16_f32 v0, v0, s0
	ds_write_b16 v48, v0 offset:52608
	v_mul_f32_e32 v0, v23, v47
	v_cvt_pk_bf16_f32 v0, v0, s0
	v_rcp_f32_e32 v33, v33
	ds_write_b16 v48, v0 offset:52672
	v_mul_f32_e32 v0, v8, v32
	v_cvt_pk_bf16_f32 v0, v0, s0
	ds_write_b16 v48, v0 offset:53248
	v_mul_f32_e32 v0, v24, v32
	v_cvt_pk_bf16_f32 v0, v0, s0
	v_rcp_f32_e32 v34, v34
	ds_write_b16 v48, v0 offset:53312
	v_mul_f32_e32 v0, v9, v33
	v_cvt_pk_bf16_f32 v0, v0, s0
	ds_write_b16 v48, v0 offset:53376
	v_mul_f32_e32 v0, v25, v33
	v_cvt_pk_bf16_f32 v0, v0, s0
	v_rcp_f32_e32 v35, v35
	ds_write_b16 v48, v0 offset:53440
	v_mul_f32_e32 v0, v10, v34
	v_cvt_pk_bf16_f32 v0, v0, s0
	ds_write_b16 v48, v0 offset:53504
	v_mul_f32_e32 v0, v26, v34
	v_cvt_pk_bf16_f32 v0, v0, s0
	s_waitcnt lgkmcnt(14)
	v_rcp_f32_e32 v36, v36
	ds_write_b16 v48, v0 offset:53568
	v_mul_f32_e32 v0, v11, v35
	v_cvt_pk_bf16_f32 v0, v0, s0
	ds_write_b16 v48, v0 offset:53632
	v_mul_f32_e32 v0, v27, v35
	v_cvt_pk_bf16_f32 v0, v0, s0
	v_rcp_f32_e32 v37, v37
	ds_write_b16 v48, v0 offset:53696
	v_mul_f32_e32 v0, v12, v36
	v_cvt_pk_bf16_f32 v0, v0, s0
	ds_write_b16 v48, v0 offset:54272
	v_mul_f32_e32 v0, v28, v36
	v_cvt_pk_bf16_f32 v0, v0, s0
	v_rcp_f32_e32 v38, v38
	ds_write_b16 v48, v0 offset:54336
	v_mul_f32_e32 v0, v13, v37
	v_cvt_pk_bf16_f32 v0, v0, s0
	ds_write_b16 v48, v0 offset:54400
	v_mul_f32_e32 v0, v29, v37
	v_cvt_pk_bf16_f32 v0, v0, s0
	v_rcp_f32_e32 v39, v39
	ds_write_b16 v48, v0 offset:54464
	v_mul_f32_e32 v0, v14, v38
	v_cvt_pk_bf16_f32 v0, v0, s0
	ds_write_b16 v48, v0 offset:54528
	v_mul_f32_e32 v0, v30, v38
	v_cvt_pk_bf16_f32 v0, v0, s0
	ds_write_b16 v48, v0 offset:54592
	v_mul_f32_e32 v0, v15, v39
	v_cvt_pk_bf16_f32 v0, v0, s0
	ds_write_b16 v48, v0 offset:54656
	v_mul_f32_e32 v0, v31, v39
	v_cvt_pk_bf16_f32 v0, v0, s0
	ds_write_b16 v48, v0 offset:54720
	s_add_u32 s6, s1, s92
	s_addc_u32 s7, s7, s93
	s_waitcnt lgkmcnt(0)
	s_add_u32 s10, s12, s92
	v_ashrrev_i32_e32 v2, 3, v178
	v_lshlrev_b32_e32 v0, 4, v178
	v_ashrrev_i32_e32 v3, 31, v2
	v_and_b32_e32 v100, 0x70, v0
	s_addc_u32 s11, s13, s93
	v_lshl_add_u64 v[0:1], s[42:43], 0, v[2:3]
	v_lshl_add_u64 v[4:5], s[10:11], 0, v[100:101]
	v_lshlrev_b64 v[0:1], 11, v[0:1]
	v_lshl_add_u64 v[0:1], v[4:5], 0, v[0:1]
	s_cselect_b32 s101, 1, 0
	s_cmp_lg_u32 s100, 0
	s_cbranch_scc1 .Lmy_fox_g1
	s_waitcnt vmcnt(0)
	s_branch .Lmy_fox_gd
.Lmy_fox_g1:
	s_cmp_lg_u32 s100, 9
	s_cbranch_scc1 .Lmy_fox_g2
	s_waitcnt vmcnt(9)
	s_branch .Lmy_fox_gd
.Lmy_fox_g2:
	s_waitcnt vmcnt(12)
.Lmy_fox_gd:
	s_cmp_lg_u32 s101, 0
	v_mov_b32_e32 v8, v208
	v_mov_b32_e32 v9, v209
	v_mov_b32_e32 v10, v210
	v_mov_b32_e32 v11, v211
	v_add_u32_e32 v6, 8, v2
	v_ashrrev_i32_e32 v7, 31, v6
	v_lshl_add_u64 v[0:1], s[42:43], 0, v[6:7]
	v_lshlrev_b64 v[0:1], 11, v[0:1]
	v_lshl_add_u64 v[0:1], v[4:5], 0, v[0:1]
	v_mov_b32_e32 v12, v226
	v_mov_b32_e32 v13, v227
	v_mov_b32_e32 v14, v228
	v_mov_b32_e32 v15, v229
	v_add_u32_e32 v32, s8, v100
	v_lshl_add_u32 v0, v2, 7, v32
	ds_read_b128 v[16:19], v0 offset:51200
	s_waitcnt lgkmcnt(0)
	v_lshlrev_b32_e32 v24, 16, v16
	v_and_b32_e32 v25, 0xffff0000, v16
	s_nop 0
	v_lshlrev_b32_e32 v20, 16, v8
	v_and_b32_e32 v21, 0xffff0000, v8
	v_mul_f32_e32 v1, 0xbfb8aa3b, v20
	v_exp_f32_e32 v1, v1
	v_mul_f32_e32 v8, 0xbfb8aa3b, v21
	v_exp_f32_e32 v8, v8
	s_nop 0
	v_lshlrev_b32_e32 v28, 16, v12
	v_add_f32_e32 v0, 1.0, v1
	v_rcp_f32_e32 v22, v0
	v_add_f32_e32 v0, 1.0, v8
	v_rcp_f32_e32 v23, v0
	v_lshl_add_u64 v[0:1], s[6:7], 0, v[100:101]
	v_and_b32_e32 v29, 0xffff0000, v12
	v_mul_f32_e32 v12, 0xbfb8aa3b, v28
	v_pk_mul_f32 v[20:21], v[22:23], v[20:21]
	v_lshlrev_b32_e32 v22, 16, v9
	v_and_b32_e32 v23, 0xffff0000, v9
	v_mul_f32_e32 v8, 0xbfb8aa3b, v22
	v_exp_f32_e32 v16, v8
	v_mul_f32_e32 v8, 0xbfb8aa3b, v23
	v_exp_f32_e32 v26, v8
	v_pk_mul_f32 v[8:9], v[20:21], v[24:25]
	v_add_f32_e32 v16, 1.0, v16
	v_rcp_f32_e32 v20, v16
	v_add_f32_e32 v16, 1.0, v26
	v_rcp_f32_e32 v21, v16
	v_cvt_pk_bf16_f32 v8, v8, v9
	v_lshlrev_b32_e32 v16, 16, v17
	v_and_b32_e32 v17, 0xffff0000, v17
	v_pk_mul_f32 v[20:21], v[20:21], v[22:23]
	v_lshlrev_b32_e32 v22, 16, v10
	v_and_b32_e32 v23, 0xffff0000, v10
	v_mul_f32_e32 v9, 0xbfb8aa3b, v22
	v_exp_f32_e32 v9, v9
	v_mul_f32_e32 v10, 0xbfb8aa3b, v23
	v_exp_f32_e32 v10, v10
	v_pk_mul_f32 v[16:17], v[20:21], v[16:17]
	v_add_f32_e32 v9, 1.0, v9
	v_rcp_f32_e32 v20, v9
	v_add_f32_e32 v9, 1.0, v10
	v_rcp_f32_e32 v21, v9
	v_add_u32_e32 v26, 16, v2
	v_cvt_pk_bf16_f32 v9, v16, v17
	v_lshlrev_b32_e32 v16, 16, v18
	v_and_b32_e32 v17, 0xffff0000, v18
	v_pk_mul_f32 v[20:21], v[20:21], v[22:23]
	v_ashrrev_i32_e32 v27, 31, v26
	v_pk_mul_f32 v[16:17], v[20:21], v[16:17]
	v_lshlrev_b32_e32 v24, 16, v11
	v_lshl_add_u64 v[20:21], s[42:43], 0, v[26:27]
	v_and_b32_e32 v25, 0xffff0000, v11
	v_mul_f32_e32 v10, 0xbfb8aa3b, v24
	v_lshlrev_b64 v[20:21], 11, v[20:21]
	v_exp_f32_e32 v11, v10
	v_mul_f32_e32 v10, 0xbfb8aa3b, v25
	v_lshl_add_u64 v[20:21], v[4:5], 0, v[20:21]
	v_exp_f32_e32 v18, v10
	v_mov_b32_e32 v20, v230
	v_mov_b32_e32 v21, v231
	v_mov_b32_e32 v22, v232
	v_mov_b32_e32 v23, v233
	v_add_f32_e32 v11, 1.0, v11
	v_cvt_pk_bf16_f32 v10, v16, v17
	v_rcp_f32_e32 v16, v11
	v_add_f32_e32 v11, 1.0, v18
	v_rcp_f32_e32 v17, v11
	v_lshlrev_b32_e32 v18, 16, v19
	v_and_b32_e32 v19, 0xffff0000, v19
	v_exp_f32_e32 v12, v12
	v_pk_mul_f32 v[16:17], v[16:17], v[24:25]
	s_nop 0
	v_pk_mul_f32 v[16:17], v[16:17], v[18:19]
	s_nop 0
	v_cvt_pk_bf16_f32 v11, v16, v17
	v_lshlrev_b64 v[16:17], 11, v[2:3]
	v_lshl_add_u64 v[24:25], v[0:1], 0, v[16:17]
	v_mul_f32_e32 v16, 0xbfb8aa3b, v29
	v_lshl_add_u32 v3, v6, 7, v32
	v_exp_f32_e32 v31, v16
	ds_read_b128 v[16:19], v3 offset:51200
	v_add_f32_e32 v3, 1.0, v12
	v_rcp_f32_e32 v30, v3
	v_add_f32_e32 v3, 1.0, v31
	v_lshlrev_b32_e32 v12, 16, v13
	v_rcp_f32_e32 v31, v3
	v_and_b32_e32 v13, 0xffff0000, v13
	v_mul_f32_e32 v3, 0xbfb8aa3b, v12
	global_store_dwordx4 v[24:25], v[8:11], off
	v_exp_f32_e32 v3, v3
	v_lshlrev_b64 v[6:7], 11, v[6:7]
	s_waitcnt lgkmcnt(0)
	v_lshlrev_b32_e32 v8, 16, v16
	v_and_b32_e32 v9, 0xffff0000, v16
	v_mul_f32_e32 v16, 0xbfb8aa3b, v13
	v_exp_f32_e32 v16, v16
	v_pk_mul_f32 v[10:11], v[30:31], v[28:29]
	v_add_f32_e32 v3, 1.0, v3
	v_pk_mul_f32 v[8:9], v[10:11], v[8:9]
	v_rcp_f32_e32 v10, v3
	v_add_f32_e32 v3, 1.0, v16
	v_rcp_f32_e32 v11, v3
	v_cvt_pk_bf16_f32 v8, v8, v9
	v_lshlrev_b32_e32 v16, 16, v17
	v_and_b32_e32 v17, 0xffff0000, v17
	v_pk_mul_f32 v[10:11], v[10:11], v[12:13]
	v_lshlrev_b32_e32 v12, 16, v14
	v_and_b32_e32 v13, 0xffff0000, v14
	v_mul_f32_e32 v3, 0xbfb8aa3b, v12
	v_exp_f32_e32 v3, v3
	v_mul_f32_e32 v9, 0xbfb8aa3b, v13
	v_exp_f32_e32 v9, v9
	v_pk_mul_f32 v[10:11], v[10:11], v[16:17]
	v_add_f32_e32 v3, 1.0, v3
	v_rcp_f32_e32 v16, v3
	v_add_f32_e32 v3, 1.0, v9
	v_rcp_f32_e32 v17, v3
	v_lshlrev_b32_e32 v14, 16, v15
	v_and_b32_e32 v15, 0xffff0000, v15
	v_mul_f32_e32 v3, 0xbfb8aa3b, v14
	v_pk_mul_f32 v[12:13], v[16:17], v[12:13]
	v_add_u32_e32 v16, 24, v2
	v_cvt_pk_bf16_f32 v9, v10, v11
	v_lshlrev_b32_e32 v10, 16, v18
	v_and_b32_e32 v11, 0xffff0000, v18
	v_exp_f32_e32 v18, v3
	v_mul_f32_e32 v3, 0xbfb8aa3b, v15
	v_ashrrev_i32_e32 v17, 31, v16
	v_exp_f32_e32 v24, v3
	v_lshl_add_u64 v[2:3], s[42:43], 0, v[16:17]
	v_lshlrev_b64 v[2:3], 11, v[2:3]
	v_lshl_add_u64 v[2:3], v[4:5], 0, v[2:3]
	v_mov_b32_e32 v2, v234
	v_mov_b32_e32 v3, v235
	v_mov_b32_e32 v4, v236
	v_mov_b32_e32 v5, v237
	v_pk_mul_f32 v[10:11], v[12:13], v[10:11]
	v_add_f32_e32 v12, 1.0, v18
	v_add_f32_e32 v13, 1.0, v24
	v_rcp_f32_e32 v12, v12
	v_rcp_f32_e32 v13, v13
	v_lshlrev_b32_e32 v18, 16, v19
	v_and_b32_e32 v19, 0xffff0000, v19
	v_cvt_pk_bf16_f32 v10, v10, v11
	v_pk_mul_f32 v[12:13], v[12:13], v[14:15]
	v_lshl_add_u64 v[6:7], v[0:1], 0, v[6:7]
	v_pk_mul_f32 v[12:13], v[12:13], v[18:19]
	s_nop 0
	v_lshlrev_b32_e32 v18, 16, v20
	v_cvt_pk_bf16_f32 v11, v12, v13
	v_and_b32_e32 v19, 0xffff0000, v20
	v_mul_f32_e32 v13, 0xbfb8aa3b, v18
	v_exp_f32_e32 v20, v13
	v_mul_f32_e32 v13, 0xbfb8aa3b, v19
	v_exp_f32_e32 v25, v13
	v_lshl_add_u32 v12, v26, 7, v32
	v_add_f32_e32 v20, 1.0, v20
	ds_read_b128 v[12:15], v12 offset:51200
	v_rcp_f32_e32 v24, v20
	v_add_f32_e32 v20, 1.0, v25
	v_rcp_f32_e32 v25, v20
	global_store_dwordx4 v[6:7], v[8:11], off
	s_waitcnt lgkmcnt(0)
	v_lshlrev_b32_e32 v6, 16, v12
	v_and_b32_e32 v7, 0xffff0000, v12
	v_lshlrev_b32_e32 v10, 16, v21
	v_and_b32_e32 v11, 0xffff0000, v21
	v_pk_mul_f32 v[8:9], v[24:25], v[18:19]
	v_mul_f32_e32 v12, 0xbfb8aa3b, v10
	v_mul_f32_e32 v18, 0xbfb8aa3b, v11
	v_exp_f32_e32 v12, v12
	v_exp_f32_e32 v18, v18
	v_pk_mul_f32 v[6:7], v[8:9], v[6:7]
	v_add_f32_e32 v8, 1.0, v12
	v_add_f32_e32 v9, 1.0, v18
	v_rcp_f32_e32 v8, v8
	v_rcp_f32_e32 v9, v9
	v_cvt_pk_bf16_f32 v6, v6, v7
	v_lshlrev_b32_e32 v12, 16, v13
	v_and_b32_e32 v13, 0xffff0000, v13
	v_pk_mul_f32 v[8:9], v[8:9], v[10:11]
	v_lshlrev_b32_e32 v10, 16, v22
	v_and_b32_e32 v11, 0xffff0000, v22
	v_mul_f32_e32 v7, 0xbfb8aa3b, v10
	v_exp_f32_e32 v7, v7
	v_mul_f32_e32 v18, 0xbfb8aa3b, v11
	v_exp_f32_e32 v18, v18
	v_pk_mul_f32 v[8:9], v[8:9], v[12:13]
	v_add_f32_e32 v7, 1.0, v7
	v_rcp_f32_e32 v12, v7
	v_add_f32_e32 v7, 1.0, v18
	v_rcp_f32_e32 v13, v7
	v_cvt_pk_bf16_f32 v7, v8, v9
	v_lshlrev_b32_e32 v8, 16, v14
	v_and_b32_e32 v9, 0xffff0000, v14
	v_pk_mul_f32 v[10:11], v[12:13], v[10:11]
	v_lshlrev_b32_e32 v12, 16, v23
	v_and_b32_e32 v13, 0xffff0000, v23
	v_mul_f32_e32 v14, 0xbfb8aa3b, v12
	v_mul_f32_e32 v18, 0xbfb8aa3b, v13
	v_exp_f32_e32 v14, v14
	v_exp_f32_e32 v18, v18
	v_pk_mul_f32 v[8:9], v[10:11], v[8:9]
	v_add_f32_e32 v10, 1.0, v14
	v_add_f32_e32 v11, 1.0, v18
	v_rcp_f32_e32 v10, v10
	v_rcp_f32_e32 v11, v11
	v_lshlrev_b32_e32 v14, 16, v15
	v_and_b32_e32 v15, 0xffff0000, v15
	v_cvt_pk_bf16_f32 v8, v8, v9
	v_pk_mul_f32 v[10:11], v[10:11], v[12:13]
	s_nop 0
	v_lshlrev_b32_e32 v18, 16, v2
	v_pk_mul_f32 v[10:11], v[10:11], v[14:15]
	v_and_b32_e32 v19, 0xffff0000, v2
	v_cvt_pk_bf16_f32 v9, v10, v11
	v_lshlrev_b64 v[10:11], 11, v[26:27]
	v_mul_f32_e32 v2, 0xbfb8aa3b, v18
	v_lshl_add_u64 v[14:15], v[0:1], 0, v[10:11]
	v_exp_f32_e32 v2, v2
	v_mul_f32_e32 v11, 0xbfb8aa3b, v19
	v_exp_f32_e32 v21, v11
	v_lshl_add_u32 v10, v16, 7, v32
	ds_read_b128 v[10:13], v10 offset:51200
	v_add_f32_e32 v2, 1.0, v2
	v_rcp_f32_e32 v20, v2
	v_add_f32_e32 v2, 1.0, v21
	v_rcp_f32_e32 v21, v2
	global_store_dwordx4 v[14:15], v[6:9], off
	v_lshlrev_b32_e32 v14, 16, v3
	v_and_b32_e32 v15, 0xffff0000, v3
	v_mul_f32_e32 v2, 0xbfb8aa3b, v14
	s_waitcnt lgkmcnt(0)
	v_lshlrev_b32_e32 v6, 16, v10
	v_and_b32_e32 v7, 0xffff0000, v10
	v_exp_f32_e32 v10, v2
	v_mul_f32_e32 v2, 0xbfb8aa3b, v15
	v_pk_mul_f32 v[8:9], v[20:21], v[18:19]
	v_exp_f32_e32 v18, v2
	v_pk_mul_f32 v[2:3], v[8:9], v[6:7]
	v_add_f32_e32 v6, 1.0, v10
	v_lshlrev_b32_e32 v10, 16, v4
	v_add_f32_e32 v7, 1.0, v18
	v_cvt_pk_bf16_f32 v2, v2, v3
	v_lshlrev_b32_e32 v8, 16, v11
	v_and_b32_e32 v9, 0xffff0000, v11
	v_and_b32_e32 v11, 0xffff0000, v4
	v_mul_f32_e32 v3, 0xbfb8aa3b, v10
	v_rcp_f32_e32 v6, v6
	v_rcp_f32_e32 v7, v7
	v_exp_f32_e32 v3, v3
	v_mul_f32_e32 v4, 0xbfb8aa3b, v11
	v_exp_f32_e32 v4, v4
	v_pk_mul_f32 v[6:7], v[6:7], v[14:15]
	v_add_f32_e32 v3, 1.0, v3
	v_pk_mul_f32 v[6:7], v[6:7], v[8:9]
	v_rcp_f32_e32 v8, v3
	v_add_f32_e32 v3, 1.0, v4
	v_rcp_f32_e32 v9, v3
	v_cvt_pk_bf16_f32 v3, v6, v7
	v_lshlrev_b32_e32 v6, 16, v12
	v_and_b32_e32 v7, 0xffff0000, v12
	v_pk_mul_f32 v[8:9], v[8:9], v[10:11]
	v_lshlrev_b32_e32 v10, 16, v5
	v_and_b32_e32 v11, 0xffff0000, v5
	v_mul_f32_e32 v4, 0xbfb8aa3b, v10
	v_exp_f32_e32 v12, v4
	v_mul_f32_e32 v4, 0xbfb8aa3b, v11
	v_exp_f32_e32 v14, v4
	v_pk_mul_f32 v[4:5], v[8:9], v[6:7]
	v_add_f32_e32 v6, 1.0, v12
	v_rcp_f32_e32 v6, v6
	v_add_f32_e32 v7, 1.0, v14
	v_rcp_f32_e32 v7, v7
	v_lshlrev_b32_e32 v8, 16, v13
	v_and_b32_e32 v9, 0xffff0000, v13
	v_cvt_pk_bf16_f32 v4, v4, v5
	v_pk_mul_f32 v[6:7], v[6:7], v[10:11]
	s_nop 0
	v_pk_mul_f32 v[6:7], v[6:7], v[8:9]
	s_nop 0
	v_cvt_pk_bf16_f32 v5, v6, v7
	v_lshlrev_b64 v[6:7], 11, v[16:17]
	v_lshl_add_u64 v[0:1], v[0:1], 0, v[6:7]
	global_store_dwordx4 v[0:1], v[2:5], off
	s_and_saveexec_b64 s[6:7], vcc
	s_cbranch_execz .LBB0_226
	s_movk_i32 s1, 0x200
	v_add_u32_e32 v0, s98, v64
	v_cmp_gt_u32_e32 vcc, s1, v64
	v_mov_b32_e32 v1, s46
	s_nop 0
	v_cndmask_b32_e32 v0, -2, v0, vcc
	ds_write_b32 v1, v0
	s_branch .LBB0_226
